# attention: reverse key-tile order (diagonal first), exact skip of exp/PV when every probability underflows to zero, heads rotated across a workgroup's units for balance
# speedup vs baseline: 1.0301x; 1.0216x over previous
; __device__ __forceinline__ float fexp2(float x) { return __builtin_amdgcn_exp2f(x); }
; __device__ __forceinline__ void attn_unit(const PT& p, LAS unsigned char* lds, int tid, int lane, int wave, int b, int hd, int qb, float lam) {
;     ...
;     const int qw0 = qb * 128 + 32 * wq, q = qw0 + r32; const unsigned tokq = (unsigned)(b * SEQ + q), tokb = (unsigned)(b * SEQ);
;     const float slope2 = fexp2(-0.5f * (float)(hd + 1)) * LOG2E;
; __device__ __forceinline__ void phase_attn(const PT& p, LAS unsigned char* lds, int tid, int lane, int wave) {
;     ...
;     for (int u = blockIdx.x; u < NBATCH * 16 * 8; u += gridDim.x) {
;         const int j = u & 7, hd = (u >> 3) & 15, b = u >> 7;
; #pragma unroll 1
;         for (int k = 0; k < 2; ++k) attn_unit(p, lds, tid, lane, wave, b, hd, k == 0 ? 15 - j : j, lam);
.LBB0_1072:
	s_and_b32 s98, s90, 0xffffffc0
	s_bfe_u32 s99, s90, 0x30003
	s_or_b32 s98, s98, s99
	s_and_b32 s99, s90, 7
	s_lshl_b32 s99, s99, 3
	s_or_b32 s98, s98, s99
	s_lshl_b32 s36, s98, 15
	s_bfe_u32 s37, s98, 0x40003
	s_lshr_b32 s99, s90, 8
	s_lshl_b32 s99, s99, 2
	s_add_i32 s37, s37, s99
	s_and_b32 s37, s37, 15
	s_and_b32 s36, s36, 0xffc00000
	s_lshl_b32 s91, s37, 7
	s_or_b32 s36, s91, s36
	s_add_i32 s37, s37, 1
	v_add_u32_e32 v235, s36, v229
	v_add_u32_e32 v236, s36, v230
	v_add_u32_e32 v237, s36, v231
	v_add_u32_e32 v238, s36, v232
	s_lshl_b32 s36, s98, 4
	v_cvt_f32_ubyte0_e32 v0, s37
	s_and_b32 s94, s36, 0xfffff800
	v_mul_f32_e32 v0, -0.5, v0
	v_exp_f32_e32 v2, v0
	v_or_b32_e32 v3, s91, v201
	v_add_u32_e32 v0, s94, v202
	v_lshl_or_b32 v50, v0, 11, v3
	v_lshlrev_b64 v[0:1], 1, v[50:51]
	v_lshl_add_u64 v[180:181], s[46:47], 0, v[0:1]
	v_lshl_add_u64 v[182:183], s[42:43], 0, v[0:1]
	v_add_u32_e32 v0, s94, v203
	v_lshl_or_b32 v50, v0, 11, v3
	v_lshlrev_b64 v[0:1], 1, v[50:51]
	v_lshl_add_u64 v[184:185], s[46:47], 0, v[0:1]
	v_lshl_add_u64 v[186:187], s[42:43], 0, v[0:1]
	v_add_u32_e32 v0, s94, v204
	v_lshl_or_b32 v50, v0, 11, v3
	v_lshlrev_b64 v[0:1], 1, v[50:51]
	v_lshl_add_u64 v[188:189], s[46:47], 0, v[0:1]
	v_lshl_add_u64 v[190:191], s[42:43], 0, v[0:1]
	v_add_u32_e32 v0, s94, v205
	v_lshl_or_b32 v50, v0, 11, v3
	s_and_b32 s92, s98, 7
	v_lshlrev_b64 v[0:1], 1, v[50:51]
	s_xor_b32 s93, s92, 15
	v_add_u32_e32 v239, s91, v200
	v_lshl_add_u64 v[192:193], s[46:47], 0, v[0:1]
	v_lshl_add_u64 v[194:195], s[42:43], 0, v[0:1]
	v_mul_f32_e32 v240, 0x3fb8aa3b, v2
	s_mov_b64 s[36:37], -1
	v_writelane_b32 v249, s38, 37
	s_branch .LBB0_1074

; #define LAS __attribute__((address_space(3)))
; __device__ __forceinline__ float fexp2(float x) { return __builtin_amdgcn_exp2f(x); }
; #define PREFETCH(t) do { \
;         _Pragma("unroll") for (int i_ = 0; i_ < 4; ++i_) { const int pid_ = tid + 512 * i_, row_ = pid_ >> 4, c16_ = pid_ & 15; const unsigned go_ = (tokb + (unsigned)((t) * 128 + row_)) * 2048u + (unsigned)(hd * 128 + 8 * c16_); \
;             preK[i_] = *(const u32x4*)(Kb + go_); preV[i_] = *(const u32x4*)(Vb + go_); } \
;     } while (0)
; #define STAGE_WRITE(stg) do { \
;         _Pragma("unroll") for (int i_ = 0; i_ < 4; ++i_) { const int pid_ = tid + 512 * i_, row_ = pid_ >> 4, c16_ = pid_ & 15; \
;             *(LAS u32x4*)(lds + (stg) * A_STAGE + A_KOFF + row_ * AK_PITCH + 16 * c16_) = preK[i_]; *(LAS u32x4*)(lds + (stg) * A_STAGE + A_VOFF + row_ * AV_PITCH + 16 * c16_) = preV[i_]; } \
;     } while (0)
; __device__ __forceinline__ void attn_unit(const PT& p, LAS unsigned char* lds, int tid, int lane, int wave, int b, int hd, int qb, float lam) {
;     ...
;     const int qw0 = qb * 128 + 32 * wq, q = qw0 + r32; const unsigned tokq = (unsigned)(b * SEQ + q), tokb = (unsigned)(b * SEQ);
;     const float slope2 = fexp2(-0.5f * (float)(hd + 1)) * LOG2E;
;     bf16x8 qf[4];
; #pragma unroll
;     for (int ds = 0; ds < 4; ++ds) qf[ds] = ld_frag16(Qb + (tokq * 2048u + (unsigned)(hd * 128 + mp * 64 + 16 * ds + 8 * h)));
;     float mrun = -INFINITY, lsum = 0.f;
;     f32x16 oT[4];
; #pragma unroll
;     for (int db = 0; db < 4; ++db)
; #pragma unroll
;         for (int i = 0; i < 16; ++i) oT[db][i] = 0.f;
;     const int ntiles = qb + 1;
;     u32x4 preV[4], preK[4];
;     ...
;     PREFETCH(0);
;     const LAS unsigned char* kbase0 = lds + A_KOFF + r32 * AK_PITCH + (mp * 64 + 8 * h) * 2;
;     const LAS unsigned char* vbase0 = lds + A_VOFF + (4 * h + ((lane & 15) >> 2)) * AV_PITCH + ((lane >> 4) & 1) * 32 + (lane & 3) * 8;
;     ...
;     __syncthreads();
;     STAGE_WRITE(0);
;     asm volatile("" : "+v"(qf[0]), "+v"(qf[1]), "+v"(qf[2]), "+v"(qf[3]));
;     __syncthreads();
.LBB0_1074:
	s_xor_b64 s[76:77], s[36:37], -1
	s_and_b64 s[36:37], s[36:37], exec
	s_cselect_b32 s95, s93, s92
	v_lshl_or_b32 v8, s95, 7, v228
	v_or_b32_e32 v0, s94, v8
	v_lshlrev_b32_e32 v241, 11, v0
	v_add_u32_e32 v50, v239, v241
	v_lshl_add_u64 v[0:1], v[50:51], 1, s[40:41]
	v_or_b32_e32 v2, 16, v50
	v_mov_b32_e32 v3, v51
	v_or_b32_e32 v4, 32, v50
	v_mov_b32_e32 v5, v51
	v_or_b32_e32 v50, 48, v50
	v_lshl_add_u64 v[2:3], v[2:3], 1, s[40:41]
	v_lshl_add_u64 v[4:5], v[4:5], 1, s[40:41]
	v_lshl_add_u64 v[6:7], v[50:51], 1, s[40:41]
	s_lshl_b32 s96, s95, 18
	s_sub_i32 s99, s96, 0x40000
	v_add_u32_e32 v50, s99, v238
	v_lshlrev_b64 v[52:53], 1, v[50:51]
	v_lshl_add_u64 v[54:55], s[46:47], 0, v[52:53]
	v_lshl_add_u64 v[52:53], s[42:43], 0, v[52:53]
	global_load_dwordx4 v[134:137], v[54:55], off
	global_load_dwordx4 v[138:141], v[52:53], off
	v_add_u32_e32 v50, s99, v237
	v_lshlrev_b64 v[52:53], 1, v[50:51]
	v_lshl_add_u64 v[54:55], s[46:47], 0, v[52:53]
	v_lshl_add_u64 v[52:53], s[42:43], 0, v[52:53]
	global_load_dwordx4 v[154:157], v[54:55], off
	global_load_dwordx4 v[158:161], v[52:53], off
	v_add_u32_e32 v50, s99, v236
	v_lshlrev_b64 v[52:53], 1, v[50:51]
	v_lshl_add_u64 v[54:55], s[46:47], 0, v[52:53]
	v_lshl_add_u64 v[52:53], s[42:43], 0, v[52:53]
	global_load_dwordx4 v[162:165], v[54:55], off
	global_load_dwordx4 v[166:169], v[52:53], off
	v_add_u32_e32 v50, s99, v235
	v_lshlrev_b64 v[52:53], 1, v[50:51]
	v_lshl_add_u64 v[54:55], s[46:47], 0, v[52:53]
	v_lshl_add_u64 v[52:53], s[42:43], 0, v[52:53]
	global_load_dwordx4 v[170:173], v[54:55], off
	global_load_dwordx4 v[174:177], v[52:53], off
	global_load_dwordx4 v[130:133], v[0:1], off
	global_load_dwordx4 v[142:145], v[6:7], off
	global_load_dwordx4 v[146:149], v[4:5], off
	global_load_dwordx4 v[150:153], v[2:3], off
	v_add_u32_e32 v0, v206, v207
	s_barrier
	v_mov_b32_e32 v64, v51
	v_mov_b32_e32 v65, v51
	s_lshl_b32 s96, s95, 18
	v_mov_b32_e32 v50, v51
	v_mov_b32_e32 v52, v51
	v_mov_b32_e32 v53, v51
	v_mov_b32_e32 v54, v51
	v_mov_b32_e32 v55, v51
	v_mov_b32_e32 v56, v51
	v_mov_b32_e32 v57, v51
	v_mov_b32_e32 v58, v51
	v_mov_b32_e32 v59, v51
	v_mov_b32_e32 v60, v51
	v_mov_b32_e32 v61, v51
	v_mov_b32_e32 v62, v51
	v_mov_b32_e32 v63, v51
	v_mov_b64_e32 v[80:81], v[64:65]
	v_mov_b64_e32 v[96:97], v[64:65]
	v_mov_b64_e32 v[112:113], v[64:65]
	v_mov_b64_e32 v[128:129], v[64:65]
	v_sub_u32_e32 v242, v178, v8
	v_lshl_add_u32 v242, s95, 7, v242
	s_mov_b32 s97, 0xfffc0000
	s_mov_b32 s38, s96
	v_mov_b32_e32 v248, 0xff800000
	v_mov_b32_e32 v243, 0
	v_mov_b64_e32 v[78:79], v[62:63]
	v_mov_b64_e32 v[76:77], v[60:61]
	v_mov_b64_e32 v[74:75], v[58:59]
	v_mov_b64_e32 v[72:73], v[56:57]
	v_mov_b64_e32 v[70:71], v[54:55]
	v_mov_b64_e32 v[68:69], v[52:53]
	v_mov_b64_e32 v[66:67], v[50:51]
	v_mov_b64_e32 v[94:95], v[62:63]
	v_mov_b64_e32 v[92:93], v[60:61]
	v_mov_b64_e32 v[90:91], v[58:59]
	v_mov_b64_e32 v[88:89], v[56:57]
	v_mov_b64_e32 v[86:87], v[54:55]
	v_mov_b64_e32 v[84:85], v[52:53]
	v_mov_b64_e32 v[82:83], v[50:51]
	v_mov_b64_e32 v[110:111], v[62:63]
	v_mov_b64_e32 v[108:109], v[60:61]
	v_mov_b64_e32 v[106:107], v[58:59]
	v_mov_b64_e32 v[104:105], v[56:57]
	v_mov_b64_e32 v[102:103], v[54:55]
	v_mov_b64_e32 v[100:101], v[52:53]
	v_mov_b64_e32 v[98:99], v[50:51]
	v_mov_b64_e32 v[126:127], v[62:63]
	v_mov_b64_e32 v[124:125], v[60:61]
	v_mov_b64_e32 v[122:123], v[58:59]
	v_mov_b64_e32 v[120:121], v[56:57]
	v_mov_b64_e32 v[118:119], v[54:55]
	v_mov_b64_e32 v[116:117], v[52:53]
	v_mov_b64_e32 v[114:115], v[50:51]
	s_mov_b32 s39, 0
	s_waitcnt vmcnt(11)
	ds_write_b128 v0, v[134:137]
	s_waitcnt vmcnt(10)
	v_bfe_u32 v2, v196, 4, 2
	v_bfe_u32 v3, v196, 6, 2
	v_sub_u32_e32 v2, v2, v3
	v_mul_i32_i24_e32 v2, 0x330, v2
	v_add_u32_e32 v3, v2, v0
	ds_write_b128 v3, v[138:141] offset:34816
	v_add_u32_e32 v0, v206, v208
	s_waitcnt vmcnt(9)
	ds_write_b128 v0, v[154:157]
	s_waitcnt vmcnt(8)
	v_add_u32_e32 v3, v2, v0
	ds_write_b128 v3, v[158:161] offset:34816
	v_add_u32_e32 v0, v206, v209
	s_waitcnt vmcnt(7)
	ds_write_b128 v0, v[162:165]
	s_waitcnt vmcnt(6)
	v_add_u32_e32 v3, v2, v0
	ds_write_b128 v3, v[166:169] offset:34816
	v_add_u32_e32 v0, v206, v210
	s_waitcnt vmcnt(5)
	ds_write_b128 v0, v[170:173]
	s_waitcnt vmcnt(4)
	v_add_u32_e32 v3, v2, v0
	ds_write_b128 v3, v[174:177] offset:34816
	s_waitcnt vmcnt(0)
	s_waitcnt lgkmcnt(0)
	s_barrier
	s_branch .LBB0_1076
; #define LAS __attribute__((address_space(3)))
; __device__ __forceinline__ f32x16 mfma32(bf16x8 a, bf16x8 b, f32x16 c) { return __builtin_amdgcn_mfma_f32_32x32x16_bf16(a, b, c, 0, 0, 0); }
; #define PREFETCH(t) do { \
;         _Pragma("unroll") for (int i_ = 0; i_ < 4; ++i_) { const int pid_ = tid + 512 * i_, row_ = pid_ >> 4, c16_ = pid_ & 15; const unsigned go_ = (tokb + (unsigned)((t) * 128 + row_)) * 2048u + (unsigned)(hd * 128 + 8 * c16_); \
;             preK[i_] = *(const u32x4*)(Kb + go_); preV[i_] = *(const u32x4*)(Vb + go_); } \
;     } while (0)
; __device__ __forceinline__ void attn_unit(const PT& p, LAS unsigned char* lds, int tid, int lane, int wave, int b, int hd, int qb, float lam) {
;     ...
;     for (int t = 0; t < ntiles; ++t) {
;         const int stg = t & 1;
;         if (t + 1 < ntiles) PREFETCH(t + 1);
;         const LAS unsigned char* kbase = kbase0 + stg * A_STAGE; const LAS unsigned char* vbase = vbase0 + stg * A_STAGE;
;         const bool diag = (t == qb);
; #pragma unroll 2
;         for (int sub = 0; sub < 2; ++sub) {
;             const int nact = diag ? min(2, max(0, wq + 1 - 2 * sub)) : 2;
;             if (nact > 0) {
;                 float sl = slope2; asm volatile("" : "+v"(sl));
;                 const float bq = sl * (float)(t * 128 + sub * 64 + 4 * h - q);
;                 const LAS unsigned char* kb0 = kbase + sub * 64 * AK_PITCH; const LAS unsigned char* vb0 = vbase + sub * 64 * AV_PITCH;
;                 f32x16 s[2];
; #pragma unroll
;                 for (int kb = 0; kb < 2; ++kb) {
;                     if (kb < nact) {
;                         const float bk = bq + sl * (float)(32 * kb);
; #pragma unroll
;                         for (int i = 0; i < 16; ++i) s[kb][i] = __builtin_fmaf(sl, (float)((i & 3) + 8 * (i >> 2)), bk);
; #pragma unroll
;                         for (int ds = 0; ds < 4; ++ds) s[kb] = mfma32(__builtin_bit_cast(bf16x8, *(const LAS u32x4*)(kb0 + kb * 32 * AK_PITCH + ds * 32)), qf[ds], s[kb]);
;                     } else {
; #pragma unroll
;                         for (int i = 0; i < 16; ++i) s[kb][i] = -INFINITY;
;                     }
;                 }
.LBB0_1075:
	s_sub_i32 s38, s38, 0x40000
	s_add_i32 s39, s39, 1
	s_cmp_eq_u32 s97, s38
	v_add_u32_e32 v242, 0xffffff80, v242
	s_waitcnt lgkmcnt(0)
	s_barrier
	s_cbranch_scc1 .LBB0_1106
.LBB0_1076:
	s_cmp_lt_u32 s39, s95
	s_cselect_b64 s[78:79], -1, 0
	s_cmp_ge_u32 s39, s95
	s_cbranch_scc1 .LBB0_1078
	s_sub_i32 s99, s38, 0x80000
	v_add_u32_e32 v50, s99, v238
	v_lshlrev_b64 v[0:1], 1, v[50:51]
	v_lshl_add_u64 v[2:3], s[46:47], 0, v[0:1]
	v_lshl_add_u64 v[0:1], s[42:43], 0, v[0:1]
	v_add_u32_e32 v50, s99, v237
	global_load_dwordx4 v[134:137], v[2:3], off
	global_load_dwordx4 v[138:141], v[0:1], off
	v_lshlrev_b64 v[0:1], 1, v[50:51]
	v_lshl_add_u64 v[2:3], s[46:47], 0, v[0:1]
	v_lshl_add_u64 v[0:1], s[42:43], 0, v[0:1]
	v_add_u32_e32 v50, s99, v236
	global_load_dwordx4 v[154:157], v[2:3], off
	global_load_dwordx4 v[158:161], v[0:1], off
	v_lshlrev_b64 v[0:1], 1, v[50:51]
	v_lshl_add_u64 v[2:3], s[46:47], 0, v[0:1]
	v_lshl_add_u64 v[0:1], s[42:43], 0, v[0:1]
	v_add_u32_e32 v50, s99, v235
	global_load_dwordx4 v[162:165], v[2:3], off
	global_load_dwordx4 v[166:169], v[0:1], off
	v_lshlrev_b64 v[0:1], 1, v[50:51]
	v_lshl_add_u64 v[2:3], s[46:47], 0, v[0:1]
	v_lshl_add_u64 v[0:1], s[42:43], 0, v[0:1]
	global_load_dwordx4 v[170:173], v[2:3], off
	global_load_dwordx4 v[174:177], v[0:1], off
.LBB0_1078:
	s_and_b32 s87, s39, 1
	s_mul_i32 s88, s87, 0x11000
	v_add_u32_e32 v56, s88, v211
	s_add_i32 s36, s88, 0x8800
	v_add_u32_e32 v254, s36, v212
	s_cmp_lg_u32 s96, s38
	s_cselect_b64 s[82:83], -1, 0
	s_cmp_eq_u32 s96, s38
	s_cselect_b64 s[80:81], -1, 0
	s_or_b64 s[84:85], s[48:49], s[82:83]
	s_and_b64 vcc, exec, s[58:59]
	s_cbranch_vccz .Lat_nostagger
	s_sleep 12
.Lat_nostagger:
	s_and_b64 s[36:37], s[82:83], exec
	s_cselect_b32 s36, 2, s33
	s_cmp_eq_u32 s36, 0
	s_cbranch_scc1 .Lat1_skip
	s_cmp_lg_u32 s36, 1
	s_cselect_b64 s[36:37], -1, 0
	ds_read_b128 v[0:3], v56 offset:17408
	ds_read_b128 v[4:7], v56 offset:17440
	ds_read_b128 v[8:11], v56 offset:17472
	ds_read_b128 v[12:15], v56 offset:17504
	v_add_u32_e32 v50, 64, v242
	v_cvt_f32_i32_e32 v50, v50
	v_mul_f32_e32 v255, v240, v50
	v_mov_b32_e32 v18, v255
	v_add_f32_e32 v19, v240, v255
	v_fma_f32 v20, v240, s62, v255
	v_fma_f32 v21, v240, s63, v255
	v_fma_f32 v22, v240, s64, v255
	v_fma_f32 v23, v240, s65, v255
	v_fma_f32 v24, v240, s66, v255
	v_fma_f32 v25, v240, s67, v255
	v_fma_f32 v26, v240, s68, v255
	v_fma_f32 v27, v240, s69, v255
	v_fma_f32 v28, v240, s70, v255
	v_fma_f32 v29, v240, s71, v255
	v_fma_f32 v30, v240, s72, v255
	v_fma_f32 v31, v240, s73, v255
	v_fma_f32 v32, v240, s74, v255
	v_fma_f32 v33, v240, s75, v255
	s_andn2_b64 vcc, exec, s[36:37]
	s_cbranch_vccnz .Lat1_k1off
	ds_read_b128 v[250:253], v56 offset:26112
	ds_read_b128 v[244:247], v56 offset:26144
	s_waitcnt lgkmcnt(5)
	v_mfma_f32_32x32x16_bf16 v[18:33], v[0:3], v[130:133], v[18:33]
	ds_read_b128 v[0:3], v56 offset:26176
	v_fmac_f32_e32 v255, 0x42000000, v240
	v_mov_b32_e32 v34, v255
	v_add_f32_e32 v35, v240, v255
	v_fma_f32 v36, v240, s62, v255
	v_fma_f32 v37, v240, s63, v255
	v_fma_f32 v38, v240, s64, v255
	s_waitcnt lgkmcnt(5)
	v_mfma_f32_32x32x16_bf16 v[18:33], v[4:7], v[150:153], v[18:33]
	ds_read_b128 v[4:7], v56 offset:26208
	v_fma_f32 v39, v240, s65, v255
	v_fma_f32 v40, v240, s66, v255
	v_fma_f32 v41, v240, s67, v255
	v_fma_f32 v42, v240, s68, v255
	v_fma_f32 v43, v240, s69, v255
	v_fma_f32 v44, v240, s70, v255
	s_waitcnt lgkmcnt(5)
	v_mfma_f32_32x32x16_bf16 v[18:33], v[8:11], v[146:149], v[18:33]
	v_fma_f32 v45, v240, s71, v255
	v_fma_f32 v46, v240, s72, v255
	v_fma_f32 v47, v240, s73, v255
	v_fma_f32 v48, v240, s74, v255
	v_fma_f32 v49, v240, s75, v255
	s_waitcnt lgkmcnt(4)
	v_mfma_f32_32x32x16_bf16 v[18:33], v[12:15], v[142:145], v[18:33]
	s_waitcnt lgkmcnt(3)
	v_mfma_f32_32x32x16_bf16 v[34:49], v[250:253], v[130:133], v[34:49]
	s_waitcnt lgkmcnt(2)
	v_mfma_f32_32x32x16_bf16 v[34:49], v[244:247], v[150:153], v[34:49]
	s_waitcnt lgkmcnt(1)
	v_mfma_f32_32x32x16_bf16 v[34:49], v[0:3], v[146:149], v[34:49]
	s_waitcnt lgkmcnt(0)
	v_mfma_f32_32x32x16_bf16 v[34:49], v[4:7], v[142:145], v[34:49]
	s_branch .Lat1_qkdone

; __device__ __forceinline__ float fexp2(float x) { return __builtin_amdgcn_exp2f(x); }
; __device__ __forceinline__ float max3f(float a, float b, float c) { return fmaxf(fmaxf(a, b), c); }
; __device__ __forceinline__ void attn_unit(const PT& p, LAS unsigned char* lds, int tid, int lane, int wave, int b, int hd, int qb, float lam) {
;     ...
;                 float mx = -INFINITY;
; #pragma unroll
;                 for (int kb = 0; kb < 2; ++kb)
; #pragma unroll
;                     for (int i = 0; i < 16; i += 2) mx = max3f(mx, s[kb][i], s[kb][i + 1]);
;                 mx = fmaxf(mx, __shfl_xor(mx, 32));
;                 const float mnew = fmaxf(mrun, mx), alpha = fexp2(mrun - mnew); mrun = mnew;
;                 float rs0 = 0.f, rs1 = 0.f, rs2 = 0.f, rs3 = 0.f;
; #pragma unroll
;                 for (int kb = 0; kb < 2; ++kb)
; #pragma unroll
;                     for (int i = 0; i < 16; i += 4) { s[kb][i] = fexp2(s[kb][i] - mnew); s[kb][i + 1] = fexp2(s[kb][i + 1] - mnew); s[kb][i + 2] = fexp2(s[kb][i + 2] - mnew); s[kb][i + 3] = fexp2(s[kb][i + 3] - mnew);
;                         rs0 += s[kb][i]; rs1 += s[kb][i + 1]; rs2 += s[kb][i + 2]; rs3 += s[kb][i + 3]; }
;                 lsum = lsum * alpha + ((rs0 + rs1) + (rs2 + rs3));
;                 if (__builtin_amdgcn_ballot_w64(alpha != 1.0f) != 0ull) {
; #pragma unroll
;                     for (int db = 0; db < 4; ++db)
; #pragma unroll
;                         for (int i = 0; i < 16; ++i) oT[db][i] *= alpha;
;                 }
.Lat1_nodiag:
	ds_read_b64_tr_b16 v[250:251], v254 offset:17408
	ds_read_b64_tr_b16 v[252:253], v254 offset:17952
	ds_read_b64_tr_b16 v[244:245], v254 offset:17472
	ds_read_b64_tr_b16 v[246:247], v254 offset:18016
	s_nop 1
	v_max3_f32 v0, v18, s89, v19
	v_max3_f32 v0, v0, v20, v21
	v_max3_f32 v0, v0, v22, v23
	v_max3_f32 v0, v0, v24, v25
	v_max3_f32 v0, v0, v26, v27
	v_max3_f32 v0, v0, v28, v29
	v_max3_f32 v0, v0, v30, v31
	v_max3_f32 v0, v0, v32, v33
	v_max3_f32 v0, v0, v34, v35
	v_max3_f32 v0, v0, v36, v37
	v_max3_f32 v0, v0, v38, v39
	v_max3_f32 v0, v0, v40, v41
	v_max3_f32 v0, v0, v42, v43
	v_max3_f32 v0, v0, v44, v45
	v_max3_f32 v0, v0, v46, v47
	v_max3_f32 v0, v0, v48, v49
	v_mov_b32_e32 v1, v0
	s_nop 1
	v_permlane32_swap_b32_e32 v0, v1
	v_max3_f32 v54, v248, v0, v1
	v_max_f32_e32 v1, v0, v1
	v_sub_f32_e32 v1, v1, v54
	v_cmp_ngt_f32_e32 vcc, 0xc3160000, v1
	s_cbranch_vccz .Lat1_zskip
	v_sub_f32_e32 v0, v248, v54
	v_exp_f32_e32 v0, v0
	s_nop 0
	v_cmp_neq_f32_e32 vcc, 1.0, v0
	s_cbranch_vccz .Lat1_noresc
	v_mul_f32_e32 v128, v0, v128
	v_mul_f32_e32 v129, v0, v129
	v_mul_f32_e32 v126, v0, v126
	v_mul_f32_e32 v127, v0, v127
	v_mul_f32_e32 v124, v0, v124
	v_mul_f32_e32 v125, v0, v125
	v_mul_f32_e32 v122, v0, v122
	v_mul_f32_e32 v123, v0, v123
	v_mul_f32_e32 v120, v0, v120
	v_mul_f32_e32 v121, v0, v121
	v_mul_f32_e32 v118, v0, v118
	v_mul_f32_e32 v119, v0, v119
	v_mul_f32_e32 v116, v0, v116
	v_mul_f32_e32 v117, v0, v117
	v_mul_f32_e32 v114, v0, v114
	v_mul_f32_e32 v115, v0, v115
	v_mul_f32_e32 v112, v0, v112
	v_mul_f32_e32 v113, v0, v113
	v_mul_f32_e32 v110, v0, v110
	v_mul_f32_e32 v111, v0, v111
	v_mul_f32_e32 v108, v0, v108
	v_mul_f32_e32 v109, v0, v109
	v_mul_f32_e32 v106, v0, v106
	v_mul_f32_e32 v107, v0, v107
	v_mul_f32_e32 v104, v0, v104
	v_mul_f32_e32 v105, v0, v105
	v_mul_f32_e32 v102, v0, v102
	v_mul_f32_e32 v103, v0, v103
	v_mul_f32_e32 v100, v0, v100
	v_mul_f32_e32 v101, v0, v101
	v_mul_f32_e32 v98, v0, v98
	v_mul_f32_e32 v99, v0, v99
	v_mul_f32_e32 v96, v0, v96
	v_mul_f32_e32 v97, v0, v97
	v_mul_f32_e32 v94, v0, v94
	v_mul_f32_e32 v95, v0, v95
	v_mul_f32_e32 v92, v0, v92
	v_mul_f32_e32 v93, v0, v93
	v_mul_f32_e32 v90, v0, v90
	v_mul_f32_e32 v91, v0, v91
	v_mul_f32_e32 v88, v0, v88
	v_mul_f32_e32 v89, v0, v89
	v_mul_f32_e32 v86, v0, v86
	v_mul_f32_e32 v87, v0, v87
	v_mul_f32_e32 v84, v0, v84
	v_mul_f32_e32 v85, v0, v85
	v_mul_f32_e32 v82, v0, v82
	v_mul_f32_e32 v83, v0, v83
	v_mul_f32_e32 v80, v0, v80
	v_mul_f32_e32 v81, v0, v81
	v_mul_f32_e32 v78, v0, v78
	v_mul_f32_e32 v79, v0, v79
	v_mul_f32_e32 v76, v0, v76
	v_mul_f32_e32 v77, v0, v77
	v_mul_f32_e32 v74, v0, v74
	v_mul_f32_e32 v75, v0, v75
	v_mul_f32_e32 v72, v0, v72
	v_mul_f32_e32 v73, v0, v73
	v_mul_f32_e32 v70, v0, v70
	v_mul_f32_e32 v71, v0, v71
	v_mul_f32_e32 v68, v0, v68
	v_mul_f32_e32 v69, v0, v69
	v_mul_f32_e32 v66, v0, v66
	v_mul_f32_e32 v67, v0, v67
; #define LAS __attribute__((address_space(3)))
; __device__ __forceinline__ float fexp2(float x) { return __builtin_amdgcn_exp2f(x); }
; __device__ __forceinline__ f32x16 mfma32(bf16x8 a, bf16x8 b, f32x16 c) { return __builtin_amdgcn_mfma_f32_32x32x16_bf16(a, b, c, 0, 0, 0); }
; __device__ __forceinline__ void attn_unit(const PT& p, LAS unsigned char* lds, int tid, int lane, int wave, int b, int hd, int qb, float lam) {
;     ...
;                 const float mnew = fmaxf(mrun, mx), alpha = fexp2(mrun - mnew); mrun = mnew;
;                 float rs0 = 0.f, rs1 = 0.f, rs2 = 0.f, rs3 = 0.f;
; #pragma unroll
;                 for (int kb = 0; kb < 2; ++kb)
; #pragma unroll
;                     for (int i = 0; i < 16; i += 4) { s[kb][i] = fexp2(s[kb][i] - mnew); s[kb][i + 1] = fexp2(s[kb][i + 1] - mnew); s[kb][i + 2] = fexp2(s[kb][i + 2] - mnew); s[kb][i + 3] = fexp2(s[kb][i + 3] - mnew);
;                         rs0 += s[kb][i]; rs1 += s[kb][i + 1]; rs2 += s[kb][i + 2]; rs3 += s[kb][i + 3]; }
;                 lsum = lsum * alpha + ((rs0 + rs1) + (rs2 + rs3));
;                 if (__builtin_amdgcn_ballot_w64(alpha != 1.0f) != 0ull) {
; #pragma unroll
;                     for (int db = 0; db < 4; ++db)
; #pragma unroll
;                         for (int i = 0; i < 16; ++i) oT[db][i] *= alpha;
;                 }
; #pragma unroll
;                 for (int kb = 0; kb < 2; ++kb) if (kb < nact) {
; #pragma unroll
;                     for (int s2 = 0; s2 < 2; ++s2) {
;                         const bf16x8 pf = pack_frag(s[kb], s2);
; #pragma unroll
;                         for (int db = 0; db < 4; ++db) {
;                             const LAS unsigned char* vp = vb0 + (kb * 32 + 16 * s2) * AV_PITCH + db * 64;
;                             const v4i16_t lo = __builtin_amdgcn_ds_read_tr16_b64_v4i16((LAS v4i16_t*)vp), hi = __builtin_amdgcn_ds_read_tr16_b64_v4i16((LAS v4i16_t*)(vp + 8 * AV_PITCH));
;                             const bf16x8 vf = {lo[0], lo[1], lo[2], lo[3], hi[0], hi[1], hi[2], hi[3]};
;                             oT[db] = mfma32(vf, pf, oT[db]);
;                         }
;                     }
;                 }
.Lat1_noresc:
	v_sub_f32_e32 v1, v18, v54
	v_sub_f32_e32 v2, v19, v54
	v_sub_f32_e32 v3, v20, v54
	v_sub_f32_e32 v4, v21, v54
	v_sub_f32_e32 v5, v22, v54
	v_sub_f32_e32 v6, v23, v54
	v_sub_f32_e32 v7, v24, v54
	v_sub_f32_e32 v8, v25, v54
	v_exp_f32_e32 v1, v1
	v_exp_f32_e32 v2, v2
	v_exp_f32_e32 v3, v3
	v_exp_f32_e32 v4, v4
	v_exp_f32_e32 v5, v5
	v_exp_f32_e32 v6, v6
	v_exp_f32_e32 v7, v7
	v_exp_f32_e32 v8, v8
	v_sub_f32_e32 v22, v38, v54
	v_sub_f32_e32 v23, v39, v54
	v_sub_f32_e32 v24, v40, v54
	v_sub_f32_e32 v25, v41, v54
	ds_read_b64_tr_b16 v[38:39], v254 offset:17536
	ds_read_b64_tr_b16 v[40:41], v254 offset:18080
	v_sub_f32_e32 v18, v34, v54
	v_sub_f32_e32 v19, v35, v54
	v_sub_f32_e32 v20, v36, v54
	v_sub_f32_e32 v21, v37, v54
	v_cvt_pk_bf16_f32 v34, v1, v2
	v_cvt_pk_bf16_f32 v35, v3, v4
	v_cvt_pk_bf16_f32 v36, v5, v6
	v_cvt_pk_bf16_f32 v37, v7, v8
	v_sub_f32_e32 v9, v26, v54
	v_sub_f32_e32 v10, v27, v54
	s_waitcnt lgkmcnt(4)
	v_mfma_f32_32x32x16_bf16 v[114:129], v[250:253], v[34:37], v[114:129]
	ds_read_b64_tr_b16 v[250:251], v254 offset:17600
	ds_read_b64_tr_b16 v[252:253], v254 offset:18144
	v_sub_f32_e32 v11, v28, v54
	v_sub_f32_e32 v12, v29, v54
	v_sub_f32_e32 v13, v30, v54
	v_sub_f32_e32 v14, v31, v54
	v_sub_f32_e32 v15, v32, v54
	v_sub_f32_e32 v17, v33, v54
	s_waitcnt lgkmcnt(4)
	v_mfma_f32_32x32x16_bf16 v[98:113], v[244:247], v[34:37], v[98:113]
	ds_read_b64_tr_b16 v[244:245], v254 offset:21760
	ds_read_b64_tr_b16 v[246:247], v254 offset:22304
	v_exp_f32_e32 v9, v9
	v_exp_f32_e32 v10, v10
	v_exp_f32_e32 v11, v11
	v_exp_f32_e32 v12, v12
	v_exp_f32_e32 v13, v13
	v_exp_f32_e32 v14, v14
	s_waitcnt lgkmcnt(4)
	v_mfma_f32_32x32x16_bf16 v[82:97], v[38:41], v[34:37], v[82:97]
	ds_read_b64_tr_b16 v[38:39], v254 offset:21824
	ds_read_b64_tr_b16 v[40:41], v254 offset:22368
	v_exp_f32_e32 v15, v15
	v_exp_f32_e32 v17, v17
	v_sub_f32_e32 v26, v42, v54
	v_sub_f32_e32 v27, v43, v54
	v_sub_f32_e32 v28, v44, v54
	v_sub_f32_e32 v29, v45, v54
	s_waitcnt lgkmcnt(4)
	v_mfma_f32_32x32x16_bf16 v[66:81], v[250:253], v[34:37], v[66:81]
	ds_read_b64_tr_b16 v[250:251], v254 offset:21888
	ds_read_b64_tr_b16 v[252:253], v254 offset:22432
	v_cvt_pk_bf16_f32 v34, v9, v10
	v_cvt_pk_bf16_f32 v35, v11, v12
	v_cvt_pk_bf16_f32 v36, v13, v14
	v_cvt_pk_bf16_f32 v37, v15, v17
	v_sub_f32_e32 v30, v46, v54
	v_sub_f32_e32 v31, v47, v54
	s_waitcnt lgkmcnt(4)
	v_mfma_f32_32x32x16_bf16 v[114:129], v[244:247], v[34:37], v[114:129]
	ds_read_b64_tr_b16 v[244:245], v254 offset:21952
	ds_read_b64_tr_b16 v[246:247], v254 offset:22496
	v_sub_f32_e32 v32, v48, v54
	v_sub_f32_e32 v33, v49, v54
	v_exp_f32_e32 v18, v18
	v_exp_f32_e32 v19, v19
	v_exp_f32_e32 v20, v20
	v_exp_f32_e32 v21, v21
	s_waitcnt lgkmcnt(4)
	v_mfma_f32_32x32x16_bf16 v[98:113], v[38:41], v[34:37], v[98:113]
	ds_read_b64_tr_b16 v[38:39], v254 offset:26112
	ds_read_b64_tr_b16 v[40:41], v254 offset:26656
	v_exp_f32_e32 v22, v22
	v_exp_f32_e32 v23, v23
	v_exp_f32_e32 v24, v24
	v_exp_f32_e32 v25, v25
	v_exp_f32_e32 v26, v26
	v_exp_f32_e32 v27, v27
	s_waitcnt lgkmcnt(4)
	v_mfma_f32_32x32x16_bf16 v[82:97], v[250:253], v[34:37], v[82:97]
	ds_read_b64_tr_b16 v[250:251], v254 offset:26176
	ds_read_b64_tr_b16 v[252:253], v254 offset:26720
	v_exp_f32_e32 v28, v28
	v_exp_f32_e32 v29, v29
	v_exp_f32_e32 v30, v30
	v_exp_f32_e32 v31, v31
	v_exp_f32_e32 v32, v32
	v_exp_f32_e32 v33, v33
	s_waitcnt lgkmcnt(4)
	v_mfma_f32_32x32x16_bf16 v[66:81], v[244:247], v[34:37], v[66:81]
	ds_read_b64_tr_b16 v[244:245], v254 offset:26240
	ds_read_b64_tr_b16 v[246:247], v254 offset:26784
	s_andn2_b64 vcc, exec, s[36:37]
	s_cbranch_vccnz .Lat1_pvk1off
	v_cvt_pk_bf16_f32 v34, v18, v19
	v_cvt_pk_bf16_f32 v35, v20, v21
	v_cvt_pk_bf16_f32 v36, v22, v23
	v_cvt_pk_bf16_f32 v37, v24, v25
	s_nop 0
	s_waitcnt lgkmcnt(4)
	v_mfma_f32_32x32x16_bf16 v[114:129], v[38:41], v[34:37], v[114:129]
	ds_read_b64_tr_b16 v[38:39], v254 offset:26304
	ds_read_b64_tr_b16 v[40:41], v254 offset:26848
	v_add_f32_e32 v1, v5, v1
	v_add_f32_e32 v2, v6, v2
	v_add_f32_e32 v3, v7, v3
	v_add_f32_e32 v4, v8, v4
	s_waitcnt lgkmcnt(4)
	v_mfma_f32_32x32x16_bf16 v[98:113], v[250:253], v[34:37], v[98:113]
	ds_read_b64_tr_b16 v[250:251], v254 offset:30464
	ds_read_b64_tr_b16 v[252:253], v254 offset:31008
	v_add_f32_e32 v1, v9, v1
	v_add_f32_e32 v2, v10, v2
	v_add_f32_e32 v3, v11, v3
	v_add_f32_e32 v4, v12, v4
	s_waitcnt lgkmcnt(4)
	v_mfma_f32_32x32x16_bf16 v[82:97], v[244:247], v[34:37], v[82:97]
	ds_read_b64_tr_b16 v[244:245], v254 offset:30528
	ds_read_b64_tr_b16 v[246:247], v254 offset:31072
	v_add_f32_e32 v1, v13, v1
	v_add_f32_e32 v2, v14, v2
	v_add_f32_e32 v3, v15, v3
	v_add_f32_e32 v4, v17, v4
	s_waitcnt lgkmcnt(4)
	v_mfma_f32_32x32x16_bf16 v[66:81], v[38:41], v[34:37], v[66:81]
	ds_read_b64_tr_b16 v[38:39], v254 offset:30592
	ds_read_b64_tr_b16 v[40:41], v254 offset:31136
	v_cvt_pk_bf16_f32 v34, v26, v27
	v_cvt_pk_bf16_f32 v35, v28, v29
	v_cvt_pk_bf16_f32 v36, v30, v31
	v_cvt_pk_bf16_f32 v37, v32, v33
	s_nop 0
	s_waitcnt lgkmcnt(4)
	v_mfma_f32_32x32x16_bf16 v[114:129], v[250:253], v[34:37], v[114:129]
	ds_read_b64_tr_b16 v[250:251], v254 offset:30656
	ds_read_b64_tr_b16 v[252:253], v254 offset:31200
	v_add_f32_e32 v1, v18, v1
	v_add_f32_e32 v2, v19, v2
	v_add_f32_e32 v3, v20, v3
	v_add_f32_e32 v4, v21, v4
	v_add_f32_e32 v1, v22, v1
	s_waitcnt lgkmcnt(4)
	v_mfma_f32_32x32x16_bf16 v[98:113], v[244:247], v[34:37], v[98:113]
	v_add_f32_e32 v2, v23, v2
	v_add_f32_e32 v3, v24, v3
	v_add_f32_e32 v4, v25, v4
	v_add_f32_e32 v1, v26, v1
	v_add_f32_e32 v2, v27, v2
	s_waitcnt lgkmcnt(2)
	v_mfma_f32_32x32x16_bf16 v[82:97], v[38:41], v[34:37], v[82:97]
	v_add_f32_e32 v3, v28, v3
	v_add_f32_e32 v4, v29, v4
	v_add_f32_e32 v1, v30, v1
	v_add_f32_e32 v2, v31, v2
	v_add_f32_e32 v3, v32, v3
	v_add_f32_e32 v4, v33, v4
	s_waitcnt lgkmcnt(0)
	v_mfma_f32_32x32x16_bf16 v[66:81], v[250:253], v[34:37], v[66:81]
	v_add_f32_e32 v1, v1, v2
	v_add_f32_e32 v2, v3, v4
	v_add_f32_e32 v53, v1, v2
	v_fmac_f32_e32 v53, v243, v0
	s_branch .Lat1_done
.Lat1_pvk1off:
	s_waitcnt lgkmcnt(0)
	v_add_f32_e32 v1, v5, v1
	v_add_f32_e32 v2, v6, v2
	v_add_f32_e32 v3, v7, v3
	v_add_f32_e32 v4, v8, v4
	v_add_f32_e32 v1, v9, v1
	v_add_f32_e32 v2, v10, v2
	v_add_f32_e32 v3, v11, v3
	v_add_f32_e32 v4, v12, v4
	v_add_f32_e32 v1, v13, v1
	v_add_f32_e32 v2, v14, v2
	v_add_f32_e32 v3, v15, v3
	v_add_f32_e32 v4, v17, v4
	v_add_f32_e32 v1, v18, v1
	v_add_f32_e32 v2, v19, v2
	v_add_f32_e32 v3, v20, v3
	v_add_f32_e32 v4, v21, v4
	v_add_f32_e32 v1, v22, v1
	v_add_f32_e32 v2, v23, v2
	v_add_f32_e32 v3, v24, v3
	v_add_f32_e32 v4, v25, v4
	v_add_f32_e32 v1, v26, v1
	v_add_f32_e32 v2, v27, v2
	v_add_f32_e32 v3, v28, v3
	v_add_f32_e32 v4, v29, v4
	v_add_f32_e32 v1, v30, v1
	v_add_f32_e32 v2, v31, v2
	v_add_f32_e32 v3, v32, v3
	v_add_f32_e32 v4, v33, v4
	v_add_f32_e32 v1, v1, v2
	v_add_f32_e32 v2, v3, v4
	v_add_f32_e32 v53, v1, v2
	v_fmac_f32_e32 v53, v243, v0
	s_branch .Lat1_done
.Lat1_skip:
	v_mov_b32_e32 v54, v248
	v_mov_b32_e32 v53, v243
	s_branch .Lat1_done
.Lat1_zskip:
	s_waitcnt lgkmcnt(0)
	v_mov_b32_e32 v53, v243

; __device__ __forceinline__ float fexp2(float x) { return __builtin_amdgcn_exp2f(x); }
; __device__ __forceinline__ float max3f(float a, float b, float c) { return fmaxf(fmaxf(a, b), c); }
; __device__ __forceinline__ void attn_unit(const PT& p, LAS unsigned char* lds, int tid, int lane, int wave, int b, int hd, int qb, float lam) {
;     ...
;                 float mx = -INFINITY;
; #pragma unroll
;                 for (int kb = 0; kb < 2; ++kb)
; #pragma unroll
;                     for (int i = 0; i < 16; i += 2) mx = max3f(mx, s[kb][i], s[kb][i + 1]);
;                 mx = fmaxf(mx, __shfl_xor(mx, 32));
;                 const float mnew = fmaxf(mrun, mx), alpha = fexp2(mrun - mnew); mrun = mnew;
;                 float rs0 = 0.f, rs1 = 0.f, rs2 = 0.f, rs3 = 0.f;
; #pragma unroll
;                 for (int kb = 0; kb < 2; ++kb)
; #pragma unroll
;                     for (int i = 0; i < 16; i += 4) { s[kb][i] = fexp2(s[kb][i] - mnew); s[kb][i + 1] = fexp2(s[kb][i + 1] - mnew); s[kb][i + 2] = fexp2(s[kb][i + 2] - mnew); s[kb][i + 3] = fexp2(s[kb][i + 3] - mnew);
;                         rs0 += s[kb][i]; rs1 += s[kb][i + 1]; rs2 += s[kb][i + 2]; rs3 += s[kb][i + 3]; }
;                 lsum = lsum * alpha + ((rs0 + rs1) + (rs2 + rs3));
;                 if (__builtin_amdgcn_ballot_w64(alpha != 1.0f) != 0ull) {
; #pragma unroll
;                     for (int db = 0; db < 4; ++db)
; #pragma unroll
;                         for (int i = 0; i < 16; ++i) oT[db][i] *= alpha;
;                 }
.Lat0_nodiag:
	ds_read_b64_tr_b16 v[250:251], v254 offset:0
	ds_read_b64_tr_b16 v[252:253], v254 offset:544
	ds_read_b64_tr_b16 v[244:245], v254 offset:64
	ds_read_b64_tr_b16 v[246:247], v254 offset:608
	s_nop 1
	v_max3_f32 v0, v18, s89, v19
	v_max3_f32 v0, v0, v20, v21
	v_max3_f32 v0, v0, v22, v23
	v_max3_f32 v0, v0, v24, v25
	v_max3_f32 v0, v0, v26, v27
	v_max3_f32 v0, v0, v28, v29
	v_max3_f32 v0, v0, v30, v31
	v_max3_f32 v0, v0, v32, v33
	v_max3_f32 v0, v0, v34, v35
	v_max3_f32 v0, v0, v36, v37
	v_max3_f32 v0, v0, v38, v39
	v_max3_f32 v0, v0, v40, v41
	v_max3_f32 v0, v0, v42, v43
	v_max3_f32 v0, v0, v44, v45
	v_max3_f32 v0, v0, v46, v47
	v_max3_f32 v0, v0, v48, v49
	v_mov_b32_e32 v1, v0
	s_nop 1
	v_permlane32_swap_b32_e32 v0, v1
	v_max3_f32 v248, v54, v0, v1
	v_max_f32_e32 v1, v0, v1
	v_sub_f32_e32 v1, v1, v248
	v_cmp_ngt_f32_e32 vcc, 0xc3160000, v1
	s_cbranch_vccz .Lat0_zskip
	v_sub_f32_e32 v0, v54, v248
	v_exp_f32_e32 v0, v0
	s_nop 0
	v_cmp_neq_f32_e32 vcc, 1.0, v0
	s_cbranch_vccz .Lat0_noresc
	v_mul_f32_e32 v128, v0, v128
	v_mul_f32_e32 v129, v0, v129
	v_mul_f32_e32 v126, v0, v126
	v_mul_f32_e32 v127, v0, v127
	v_mul_f32_e32 v124, v0, v124
	v_mul_f32_e32 v125, v0, v125
	v_mul_f32_e32 v122, v0, v122
	v_mul_f32_e32 v123, v0, v123
	v_mul_f32_e32 v120, v0, v120
	v_mul_f32_e32 v121, v0, v121
	v_mul_f32_e32 v118, v0, v118
	v_mul_f32_e32 v119, v0, v119
	v_mul_f32_e32 v116, v0, v116
	v_mul_f32_e32 v117, v0, v117
	v_mul_f32_e32 v114, v0, v114
	v_mul_f32_e32 v115, v0, v115
	v_mul_f32_e32 v112, v0, v112
	v_mul_f32_e32 v113, v0, v113
	v_mul_f32_e32 v110, v0, v110
	v_mul_f32_e32 v111, v0, v111
	v_mul_f32_e32 v108, v0, v108
	v_mul_f32_e32 v109, v0, v109
	v_mul_f32_e32 v106, v0, v106
	v_mul_f32_e32 v107, v0, v107
	v_mul_f32_e32 v104, v0, v104
	v_mul_f32_e32 v105, v0, v105
	v_mul_f32_e32 v102, v0, v102
	v_mul_f32_e32 v103, v0, v103
	v_mul_f32_e32 v100, v0, v100
	v_mul_f32_e32 v101, v0, v101
	v_mul_f32_e32 v98, v0, v98
	v_mul_f32_e32 v99, v0, v99
	v_mul_f32_e32 v96, v0, v96
	v_mul_f32_e32 v97, v0, v97
	v_mul_f32_e32 v94, v0, v94
	v_mul_f32_e32 v95, v0, v95
	v_mul_f32_e32 v92, v0, v92
	v_mul_f32_e32 v93, v0, v93
	v_mul_f32_e32 v90, v0, v90
	v_mul_f32_e32 v91, v0, v91
	v_mul_f32_e32 v88, v0, v88
	v_mul_f32_e32 v89, v0, v89
	v_mul_f32_e32 v86, v0, v86
	v_mul_f32_e32 v87, v0, v87
	v_mul_f32_e32 v84, v0, v84
	v_mul_f32_e32 v85, v0, v85
	v_mul_f32_e32 v82, v0, v82
	v_mul_f32_e32 v83, v0, v83
	v_mul_f32_e32 v80, v0, v80
	v_mul_f32_e32 v81, v0, v81
	v_mul_f32_e32 v78, v0, v78
	v_mul_f32_e32 v79, v0, v79
	v_mul_f32_e32 v76, v0, v76
	v_mul_f32_e32 v77, v0, v77
	v_mul_f32_e32 v74, v0, v74
	v_mul_f32_e32 v75, v0, v75
	v_mul_f32_e32 v72, v0, v72
	v_mul_f32_e32 v73, v0, v73
	v_mul_f32_e32 v70, v0, v70
	v_mul_f32_e32 v71, v0, v71
	v_mul_f32_e32 v68, v0, v68
	v_mul_f32_e32 v69, v0, v69
	v_mul_f32_e32 v66, v0, v66
	v_mul_f32_e32 v67, v0, v67
; #define LAS __attribute__((address_space(3)))
; __device__ __forceinline__ float fexp2(float x) { return __builtin_amdgcn_exp2f(x); }
; __device__ __forceinline__ f32x16 mfma32(bf16x8 a, bf16x8 b, f32x16 c) { return __builtin_amdgcn_mfma_f32_32x32x16_bf16(a, b, c, 0, 0, 0); }
; __device__ __forceinline__ void attn_unit(const PT& p, LAS unsigned char* lds, int tid, int lane, int wave, int b, int hd, int qb, float lam) {
;     ...
;                 const float mnew = fmaxf(mrun, mx), alpha = fexp2(mrun - mnew); mrun = mnew;
;                 float rs0 = 0.f, rs1 = 0.f, rs2 = 0.f, rs3 = 0.f;
; #pragma unroll
;                 for (int kb = 0; kb < 2; ++kb)
; #pragma unroll
;                     for (int i = 0; i < 16; i += 4) { s[kb][i] = fexp2(s[kb][i] - mnew); s[kb][i + 1] = fexp2(s[kb][i + 1] - mnew); s[kb][i + 2] = fexp2(s[kb][i + 2] - mnew); s[kb][i + 3] = fexp2(s[kb][i + 3] - mnew);
;                         rs0 += s[kb][i]; rs1 += s[kb][i + 1]; rs2 += s[kb][i + 2]; rs3 += s[kb][i + 3]; }
;                 lsum = lsum * alpha + ((rs0 + rs1) + (rs2 + rs3));
;                 if (__builtin_amdgcn_ballot_w64(alpha != 1.0f) != 0ull) {
; #pragma unroll
;                     for (int db = 0; db < 4; ++db)
; #pragma unroll
;                         for (int i = 0; i < 16; ++i) oT[db][i] *= alpha;
;                 }
; #pragma unroll
;                 for (int kb = 0; kb < 2; ++kb) if (kb < nact) {
; #pragma unroll
;                     for (int s2 = 0; s2 < 2; ++s2) {
;                         const bf16x8 pf = pack_frag(s[kb], s2);
; #pragma unroll
;                         for (int db = 0; db < 4; ++db) {
;                             const LAS unsigned char* vp = vb0 + (kb * 32 + 16 * s2) * AV_PITCH + db * 64;
;                             const v4i16_t lo = __builtin_amdgcn_ds_read_tr16_b64_v4i16((LAS v4i16_t*)vp), hi = __builtin_amdgcn_ds_read_tr16_b64_v4i16((LAS v4i16_t*)(vp + 8 * AV_PITCH));
;                             const bf16x8 vf = {lo[0], lo[1], lo[2], lo[3], hi[0], hi[1], hi[2], hi[3]};
;                             oT[db] = mfma32(vf, pf, oT[db]);
;                         }
;                     }
;                 }
.Lat0_noresc:
	v_sub_f32_e32 v1, v18, v248
	v_sub_f32_e32 v2, v19, v248
	v_sub_f32_e32 v3, v20, v248
	v_sub_f32_e32 v4, v21, v248
	v_sub_f32_e32 v5, v22, v248
	v_sub_f32_e32 v6, v23, v248
	v_sub_f32_e32 v7, v24, v248
	v_sub_f32_e32 v8, v25, v248
	v_exp_f32_e32 v1, v1
	v_exp_f32_e32 v2, v2
	v_exp_f32_e32 v3, v3
	v_exp_f32_e32 v4, v4
	v_exp_f32_e32 v5, v5
	v_exp_f32_e32 v6, v6
	v_exp_f32_e32 v7, v7
	v_exp_f32_e32 v8, v8
	v_sub_f32_e32 v22, v38, v248
	v_sub_f32_e32 v23, v39, v248
	v_sub_f32_e32 v24, v40, v248
	v_sub_f32_e32 v25, v41, v248
	ds_read_b64_tr_b16 v[38:39], v254 offset:128
	ds_read_b64_tr_b16 v[40:41], v254 offset:672
	v_sub_f32_e32 v18, v34, v248
	v_sub_f32_e32 v19, v35, v248
	v_sub_f32_e32 v20, v36, v248
	v_sub_f32_e32 v21, v37, v248
	v_cvt_pk_bf16_f32 v34, v1, v2
	v_cvt_pk_bf16_f32 v35, v3, v4
	v_cvt_pk_bf16_f32 v36, v5, v6
	v_cvt_pk_bf16_f32 v37, v7, v8
	v_sub_f32_e32 v9, v26, v248
	v_sub_f32_e32 v10, v27, v248
	s_waitcnt lgkmcnt(4)
	v_mfma_f32_32x32x16_bf16 v[114:129], v[250:253], v[34:37], v[114:129]
	ds_read_b64_tr_b16 v[250:251], v254 offset:192
	ds_read_b64_tr_b16 v[252:253], v254 offset:736
	v_sub_f32_e32 v11, v28, v248
	v_sub_f32_e32 v12, v29, v248
	v_sub_f32_e32 v13, v30, v248
	v_sub_f32_e32 v14, v31, v248
	v_sub_f32_e32 v15, v32, v248
	v_sub_f32_e32 v17, v33, v248
	s_waitcnt lgkmcnt(4)
	v_mfma_f32_32x32x16_bf16 v[98:113], v[244:247], v[34:37], v[98:113]
	ds_read_b64_tr_b16 v[244:245], v254 offset:4352
	ds_read_b64_tr_b16 v[246:247], v254 offset:4896
	v_exp_f32_e32 v9, v9
	v_exp_f32_e32 v10, v10
	v_exp_f32_e32 v11, v11
	v_exp_f32_e32 v12, v12
	v_exp_f32_e32 v13, v13
	v_exp_f32_e32 v14, v14
	s_waitcnt lgkmcnt(4)
	v_mfma_f32_32x32x16_bf16 v[82:97], v[38:41], v[34:37], v[82:97]
	ds_read_b64_tr_b16 v[38:39], v254 offset:4416
	ds_read_b64_tr_b16 v[40:41], v254 offset:4960
	v_exp_f32_e32 v15, v15
	v_exp_f32_e32 v17, v17
	v_sub_f32_e32 v26, v42, v248
	v_sub_f32_e32 v27, v43, v248
	v_sub_f32_e32 v28, v44, v248
	v_sub_f32_e32 v29, v45, v248
	s_waitcnt lgkmcnt(4)
	v_mfma_f32_32x32x16_bf16 v[66:81], v[250:253], v[34:37], v[66:81]
	ds_read_b64_tr_b16 v[250:251], v254 offset:4480
	ds_read_b64_tr_b16 v[252:253], v254 offset:5024
	v_cvt_pk_bf16_f32 v34, v9, v10
	v_cvt_pk_bf16_f32 v35, v11, v12
	v_cvt_pk_bf16_f32 v36, v13, v14
	v_cvt_pk_bf16_f32 v37, v15, v17
	v_sub_f32_e32 v30, v46, v248
	v_sub_f32_e32 v31, v47, v248
	s_waitcnt lgkmcnt(4)
	v_mfma_f32_32x32x16_bf16 v[114:129], v[244:247], v[34:37], v[114:129]
	ds_read_b64_tr_b16 v[244:245], v254 offset:4544
	ds_read_b64_tr_b16 v[246:247], v254 offset:5088
	v_sub_f32_e32 v32, v48, v248
	v_sub_f32_e32 v33, v49, v248
	v_exp_f32_e32 v18, v18
	v_exp_f32_e32 v19, v19
	v_exp_f32_e32 v20, v20
	v_exp_f32_e32 v21, v21
	s_waitcnt lgkmcnt(4)
	v_mfma_f32_32x32x16_bf16 v[98:113], v[38:41], v[34:37], v[98:113]
	ds_read_b64_tr_b16 v[38:39], v254 offset:8704
	ds_read_b64_tr_b16 v[40:41], v254 offset:9248
	v_exp_f32_e32 v22, v22
	v_exp_f32_e32 v23, v23
	v_exp_f32_e32 v24, v24
	v_exp_f32_e32 v25, v25
	v_exp_f32_e32 v26, v26
	v_exp_f32_e32 v27, v27
	s_waitcnt lgkmcnt(4)
	v_mfma_f32_32x32x16_bf16 v[82:97], v[250:253], v[34:37], v[82:97]
	ds_read_b64_tr_b16 v[250:251], v254 offset:8768
	ds_read_b64_tr_b16 v[252:253], v254 offset:9312
	v_exp_f32_e32 v28, v28
	v_exp_f32_e32 v29, v29
	v_exp_f32_e32 v30, v30
	v_exp_f32_e32 v31, v31
	v_exp_f32_e32 v32, v32
	v_exp_f32_e32 v33, v33
	s_waitcnt lgkmcnt(4)
	v_mfma_f32_32x32x16_bf16 v[66:81], v[244:247], v[34:37], v[66:81]
	ds_read_b64_tr_b16 v[244:245], v254 offset:8832
	ds_read_b64_tr_b16 v[246:247], v254 offset:9376
	s_andn2_b64 vcc, exec, s[84:85]
	s_cbranch_vccnz .Lat0_pvk1off
	v_cvt_pk_bf16_f32 v34, v18, v19
	v_cvt_pk_bf16_f32 v35, v20, v21
	v_cvt_pk_bf16_f32 v36, v22, v23
	v_cvt_pk_bf16_f32 v37, v24, v25
	s_nop 0
	s_waitcnt lgkmcnt(4)
	v_mfma_f32_32x32x16_bf16 v[114:129], v[38:41], v[34:37], v[114:129]
	ds_read_b64_tr_b16 v[38:39], v254 offset:8896
	ds_read_b64_tr_b16 v[40:41], v254 offset:9440
	v_add_f32_e32 v1, v5, v1
	v_add_f32_e32 v2, v6, v2
	v_add_f32_e32 v3, v7, v3
	v_add_f32_e32 v4, v8, v4
	s_waitcnt lgkmcnt(4)
	v_mfma_f32_32x32x16_bf16 v[98:113], v[250:253], v[34:37], v[98:113]
	ds_read_b64_tr_b16 v[250:251], v254 offset:13056
	ds_read_b64_tr_b16 v[252:253], v254 offset:13600
	v_add_f32_e32 v1, v9, v1
	v_add_f32_e32 v2, v10, v2
	v_add_f32_e32 v3, v11, v3
	v_add_f32_e32 v4, v12, v4
	s_waitcnt lgkmcnt(4)
	v_mfma_f32_32x32x16_bf16 v[82:97], v[244:247], v[34:37], v[82:97]
	ds_read_b64_tr_b16 v[244:245], v254 offset:13120
	ds_read_b64_tr_b16 v[246:247], v254 offset:13664
	v_add_f32_e32 v1, v13, v1
	v_add_f32_e32 v2, v14, v2
	v_add_f32_e32 v3, v15, v3
	v_add_f32_e32 v4, v17, v4
	s_waitcnt lgkmcnt(4)
	v_mfma_f32_32x32x16_bf16 v[66:81], v[38:41], v[34:37], v[66:81]
	ds_read_b64_tr_b16 v[38:39], v254 offset:13184
	ds_read_b64_tr_b16 v[40:41], v254 offset:13728
	v_cvt_pk_bf16_f32 v34, v26, v27
	v_cvt_pk_bf16_f32 v35, v28, v29
	v_cvt_pk_bf16_f32 v36, v30, v31
	v_cvt_pk_bf16_f32 v37, v32, v33
	s_nop 0
	s_waitcnt lgkmcnt(4)
	v_mfma_f32_32x32x16_bf16 v[114:129], v[250:253], v[34:37], v[114:129]
	ds_read_b64_tr_b16 v[250:251], v254 offset:13248
	ds_read_b64_tr_b16 v[252:253], v254 offset:13792
	v_add_f32_e32 v1, v18, v1
	v_add_f32_e32 v2, v19, v2
	v_add_f32_e32 v3, v20, v3
	v_add_f32_e32 v4, v21, v4
	v_add_f32_e32 v1, v22, v1
	s_waitcnt lgkmcnt(4)
	v_mfma_f32_32x32x16_bf16 v[98:113], v[244:247], v[34:37], v[98:113]
	v_add_f32_e32 v2, v23, v2
	v_add_f32_e32 v3, v24, v3
	v_add_f32_e32 v4, v25, v4
	v_add_f32_e32 v1, v26, v1
	v_add_f32_e32 v2, v27, v2
	s_waitcnt lgkmcnt(2)
	v_mfma_f32_32x32x16_bf16 v[82:97], v[38:41], v[34:37], v[82:97]
	v_add_f32_e32 v3, v28, v3
	v_add_f32_e32 v4, v29, v4
	v_add_f32_e32 v1, v30, v1
	v_add_f32_e32 v2, v31, v2
	v_add_f32_e32 v3, v32, v3
	v_add_f32_e32 v4, v33, v4
	s_waitcnt lgkmcnt(0)
	v_mfma_f32_32x32x16_bf16 v[66:81], v[250:253], v[34:37], v[66:81]
	v_add_f32_e32 v1, v1, v2
	v_add_f32_e32 v2, v3, v4
	v_add_f32_e32 v243, v1, v2
	v_fmac_f32_e32 v243, v53, v0
	s_branch .Lat0_done

; __device__ __forceinline__ float fexp2(float x) { return __builtin_amdgcn_exp2f(x); }
; __device__ __forceinline__ void attn_unit(const PT& p, LAS unsigned char* lds, int tid, int lane, int wave, int b, int hd, int qb, float lam) {
;     ...
;                 const float mnew = fmaxf(mrun, mx), alpha = fexp2(mrun - mnew); mrun = mnew;
;                 float rs0 = 0.f, rs1 = 0.f, rs2 = 0.f, rs3 = 0.f;
; #pragma unroll
;                 for (int kb = 0; kb < 2; ++kb)
; #pragma unroll
;                     for (int i = 0; i < 16; i += 4) { s[kb][i] = fexp2(s[kb][i] - mnew); s[kb][i + 1] = fexp2(s[kb][i + 1] - mnew); s[kb][i + 2] = fexp2(s[kb][i + 2] - mnew); s[kb][i + 3] = fexp2(s[kb][i + 3] - mnew);
;                         rs0 += s[kb][i]; rs1 += s[kb][i + 1]; rs2 += s[kb][i + 2]; rs3 += s[kb][i + 3]; }
;                 lsum = lsum * alpha + ((rs0 + rs1) + (rs2 + rs3));
.Lat0_zskip:
	s_waitcnt lgkmcnt(0)
	v_mov_b32_e32 v243, v53
